# final_norm rewritten: 16-byte row loads (8 columns per lane), row partial sums by one dword per lane + DPP row reduce, gain hoisted, loads two rows ahead; scan prescale
# baseline (speedup 1.0000x reference)
.LBB0_1888:
	s_or_b64 exec, exec, s[4:5]
	s_waitcnt lgkmcnt(0)
	v_mov_b32_e32 v0, v154
	s_barrier
	s_load_dwordx4 s[4:7], s[0:1], 0x128
	s_load_dwordx2 s[10:11], s[0:1], 0x138
	v_readfirstlane_b32 s3, v154
	s_lshr_b32 s3, s3, 6
	s_lshl_b32 s2, s2, 3
	s_add_i32 s2, s2, s3
	v_and_b32_e32 v60, 63, v154
	v_lshlrev_b32_e32 v61, 4, v60
	v_lshlrev_b32_e32 v62, 5, v60
	v_and_b32_e32 v63, 15, v154
	v_lshlrev_b32_e32 v63, 2, v63
	v_mov_b32_e32 v59, 0x358637bd
	s_waitcnt lgkmcnt(0)
	global_load_dwordx4 v[40:43], v62, s[4:5]
	global_load_dwordx4 v[44:47], v62, s[4:5] offset:16
	global_load_dwordx4 v[48:51], v62, s[4:5] offset:2048
	global_load_dwordx4 v[52:55], v62, s[4:5] offset:2064
	s_add_i32 s12, s2, 0x0
	s_lshl_b32 s13, s12, 11
	s_add_u32 s14, s10, s13
	s_addc_u32 s15, s11, 0
	s_add_u32 s14, s14, 0x6b00000
	s_addc_u32 s15, s15, 0
	s_lshl_b32 s13, s12, 6
	s_add_u32 s16, s10, s13
	s_addc_u32 s17, s11, 0
	s_add_u32 s16, s16, 0xfe00000
	s_addc_u32 s17, s17, 0
	global_load_dwordx4 v[0:3], v61, s[14:15]
	global_load_dwordx4 v[4:7], v61, s[14:15] offset:1024
	global_load_dword v8, v63, s[16:17]
	s_add_i32 s12, s2, 0x800
	s_lshl_b32 s13, s12, 11
	s_add_u32 s14, s10, s13
	s_addc_u32 s15, s11, 0
	s_add_u32 s14, s14, 0x6b00000
	s_addc_u32 s15, s15, 0
	s_lshl_b32 s13, s12, 6
	s_add_u32 s16, s10, s13
	s_addc_u32 s17, s11, 0
	s_add_u32 s16, s16, 0xfe00000
	s_addc_u32 s17, s17, 0
	global_load_dwordx4 v[10:13], v61, s[14:15]
	global_load_dwordx4 v[14:17], v61, s[14:15] offset:1024
	global_load_dword v18, v63, s[16:17]
	s_add_i32 s12, s2, 0x1000
	s_lshl_b32 s13, s12, 11
	s_add_u32 s14, s10, s13
	s_addc_u32 s15, s11, 0
	s_add_u32 s14, s14, 0x6b00000
	s_addc_u32 s15, s15, 0
	s_lshl_b32 s13, s12, 6
	s_add_u32 s16, s10, s13
	s_addc_u32 s17, s11, 0
	s_add_u32 s16, s16, 0xfe00000
	s_addc_u32 s17, s17, 0
	global_load_dwordx4 v[20:23], v61, s[14:15]
	global_load_dwordx4 v[24:27], v61, s[14:15] offset:1024
	global_load_dword v28, v63, s[16:17]
	s_waitcnt vmcnt(6)
	s_nop 0
	v_add_f32_dpp v8, v8, v8 row_ror:8 row_mask:0xf bank_mask:0xf
	s_nop 1
	v_add_f32_dpp v8, v8, v8 row_ror:4 row_mask:0xf bank_mask:0xf
	s_nop 1
	v_add_f32_dpp v8, v8, v8 row_ror:2 row_mask:0xf bank_mask:0xf
	s_nop 1
	v_add_f32_dpp v8, v8, v8 row_ror:1 row_mask:0xf bank_mask:0xf
	s_nop 1
	v_fmamk_f32 v8, v8, 0x3a800000, v59
	v_rsq_f32_e32 v8, v8
	v_lshlrev_b32_e32 v30, 16, v0
	v_and_b32_e32 v31, 0xffff0000, v0
	v_lshlrev_b32_e32 v32, 16, v1
	v_and_b32_e32 v33, 0xffff0000, v1
	v_lshlrev_b32_e32 v34, 16, v2
	v_and_b32_e32 v35, 0xffff0000, v2
	v_lshlrev_b32_e32 v36, 16, v3
	v_and_b32_e32 v37, 0xffff0000, v3
	v_mul_f32_e32 v30, v8, v30
	v_mul_f32_e32 v31, v8, v31
	v_mul_f32_e32 v32, v8, v32
	v_mul_f32_e32 v33, v8, v33
	v_mul_f32_e32 v34, v8, v34
	v_mul_f32_e32 v35, v8, v35
	v_mul_f32_e32 v36, v8, v36
	v_mul_f32_e32 v37, v8, v37
	v_mul_f32_e32 v64, v40, v30
	v_mul_f32_e32 v65, v41, v31
	v_mul_f32_e32 v66, v42, v32
	v_mul_f32_e32 v67, v43, v33
	v_mul_f32_e32 v68, v44, v34
	v_mul_f32_e32 v69, v45, v35
	v_mul_f32_e32 v70, v46, v36
	v_mul_f32_e32 v71, v47, v37
	v_lshlrev_b32_e32 v30, 16, v4
	v_and_b32_e32 v31, 0xffff0000, v4
	v_lshlrev_b32_e32 v32, 16, v5
	v_and_b32_e32 v33, 0xffff0000, v5
	v_lshlrev_b32_e32 v34, 16, v6
	v_and_b32_e32 v35, 0xffff0000, v6
	v_lshlrev_b32_e32 v36, 16, v7
	v_and_b32_e32 v37, 0xffff0000, v7
	v_mul_f32_e32 v30, v8, v30
	v_mul_f32_e32 v31, v8, v31
	v_mul_f32_e32 v32, v8, v32
	v_mul_f32_e32 v33, v8, v33
	v_mul_f32_e32 v34, v8, v34
	v_mul_f32_e32 v35, v8, v35
	v_mul_f32_e32 v36, v8, v36
	v_mul_f32_e32 v37, v8, v37
	v_mul_f32_e32 v72, v48, v30
	v_mul_f32_e32 v73, v49, v31
	v_mul_f32_e32 v74, v50, v32
	v_mul_f32_e32 v75, v51, v33
	v_mul_f32_e32 v76, v52, v34
	v_mul_f32_e32 v77, v53, v35
	v_mul_f32_e32 v78, v54, v36
	v_mul_f32_e32 v79, v55, v37
	s_add_i32 s12, s2, 0x0
	s_lshl_b32 s13, s12, 12
	s_add_u32 s18, s6, s13
	s_addc_u32 s19, s7, 0
	global_store_dwordx4 v62, v[64:67], s[18:19]
	global_store_dwordx4 v62, v[68:71], s[18:19] offset:16
	global_store_dwordx4 v62, v[72:75], s[18:19] offset:2048
	global_store_dwordx4 v62, v[76:79], s[18:19] offset:2064
	s_add_i32 s12, s2, 0x1800
	s_lshl_b32 s13, s12, 11
	s_add_u32 s14, s10, s13
	s_addc_u32 s15, s11, 0
	s_add_u32 s14, s14, 0x6b00000
	s_addc_u32 s15, s15, 0
	s_lshl_b32 s13, s12, 6
	s_add_u32 s16, s10, s13
	s_addc_u32 s17, s11, 0
	s_add_u32 s16, s16, 0xfe00000
	s_addc_u32 s17, s17, 0
	global_load_dwordx4 v[0:3], v61, s[14:15]
	global_load_dwordx4 v[4:7], v61, s[14:15] offset:1024
	global_load_dword v8, v63, s[16:17]
	s_waitcnt vmcnt(10)
	s_nop 0
	v_add_f32_dpp v18, v18, v18 row_ror:8 row_mask:0xf bank_mask:0xf
	s_nop 1
	v_add_f32_dpp v18, v18, v18 row_ror:4 row_mask:0xf bank_mask:0xf
	s_nop 1
	v_add_f32_dpp v18, v18, v18 row_ror:2 row_mask:0xf bank_mask:0xf
	s_nop 1
	v_add_f32_dpp v18, v18, v18 row_ror:1 row_mask:0xf bank_mask:0xf
	s_nop 1
	v_fmamk_f32 v18, v18, 0x3a800000, v59
	v_rsq_f32_e32 v18, v18
	v_lshlrev_b32_e32 v30, 16, v10
	v_and_b32_e32 v31, 0xffff0000, v10
	v_lshlrev_b32_e32 v32, 16, v11
	v_and_b32_e32 v33, 0xffff0000, v11
	v_lshlrev_b32_e32 v34, 16, v12
	v_and_b32_e32 v35, 0xffff0000, v12
	v_lshlrev_b32_e32 v36, 16, v13
	v_and_b32_e32 v37, 0xffff0000, v13
	v_mul_f32_e32 v30, v18, v30
	v_mul_f32_e32 v31, v18, v31
	v_mul_f32_e32 v32, v18, v32
	v_mul_f32_e32 v33, v18, v33
	v_mul_f32_e32 v34, v18, v34
	v_mul_f32_e32 v35, v18, v35
	v_mul_f32_e32 v36, v18, v36
	v_mul_f32_e32 v37, v18, v37
	v_mul_f32_e32 v80, v40, v30
	v_mul_f32_e32 v81, v41, v31
	v_mul_f32_e32 v82, v42, v32
	v_mul_f32_e32 v83, v43, v33
	v_mul_f32_e32 v84, v44, v34
	v_mul_f32_e32 v85, v45, v35
	v_mul_f32_e32 v86, v46, v36
	v_mul_f32_e32 v87, v47, v37
	v_lshlrev_b32_e32 v30, 16, v14
	v_and_b32_e32 v31, 0xffff0000, v14
	v_lshlrev_b32_e32 v32, 16, v15
	v_and_b32_e32 v33, 0xffff0000, v15
	v_lshlrev_b32_e32 v34, 16, v16
	v_and_b32_e32 v35, 0xffff0000, v16
	v_lshlrev_b32_e32 v36, 16, v17
	v_and_b32_e32 v37, 0xffff0000, v17
	v_mul_f32_e32 v30, v18, v30
	v_mul_f32_e32 v31, v18, v31
	v_mul_f32_e32 v32, v18, v32
	v_mul_f32_e32 v33, v18, v33
	v_mul_f32_e32 v34, v18, v34
	v_mul_f32_e32 v35, v18, v35
	v_mul_f32_e32 v36, v18, v36
	v_mul_f32_e32 v37, v18, v37
	v_mul_f32_e32 v88, v48, v30
	v_mul_f32_e32 v89, v49, v31
	v_mul_f32_e32 v90, v50, v32
	v_mul_f32_e32 v91, v51, v33
	v_mul_f32_e32 v92, v52, v34
	v_mul_f32_e32 v93, v53, v35
	v_mul_f32_e32 v94, v54, v36
	v_mul_f32_e32 v95, v55, v37
	s_add_i32 s12, s2, 0x800
	s_lshl_b32 s13, s12, 12
	s_add_u32 s18, s6, s13
	s_addc_u32 s19, s7, 0
	global_store_dwordx4 v62, v[80:83], s[18:19]
	global_store_dwordx4 v62, v[84:87], s[18:19] offset:16
	global_store_dwordx4 v62, v[88:91], s[18:19] offset:2048
	global_store_dwordx4 v62, v[92:95], s[18:19] offset:2064
	s_add_i32 s12, s2, 0x2000
	s_lshl_b32 s13, s12, 11
	s_add_u32 s14, s10, s13
	s_addc_u32 s15, s11, 0
	s_add_u32 s14, s14, 0x6b00000
	s_addc_u32 s15, s15, 0
	s_lshl_b32 s13, s12, 6
	s_add_u32 s16, s10, s13
	s_addc_u32 s17, s11, 0
	s_add_u32 s16, s16, 0xfe00000
	s_addc_u32 s17, s17, 0
	global_load_dwordx4 v[10:13], v61, s[14:15]
	global_load_dwordx4 v[14:17], v61, s[14:15] offset:1024
	global_load_dword v18, v63, s[16:17]
	s_waitcnt vmcnt(14)
	s_nop 0
	v_add_f32_dpp v28, v28, v28 row_ror:8 row_mask:0xf bank_mask:0xf
	s_nop 1
	v_add_f32_dpp v28, v28, v28 row_ror:4 row_mask:0xf bank_mask:0xf
	s_nop 1
	v_add_f32_dpp v28, v28, v28 row_ror:2 row_mask:0xf bank_mask:0xf
	s_nop 1
	v_add_f32_dpp v28, v28, v28 row_ror:1 row_mask:0xf bank_mask:0xf
	s_nop 1
	v_fmamk_f32 v28, v28, 0x3a800000, v59
	v_rsq_f32_e32 v28, v28
	v_lshlrev_b32_e32 v30, 16, v20
	v_and_b32_e32 v31, 0xffff0000, v20
	v_lshlrev_b32_e32 v32, 16, v21
	v_and_b32_e32 v33, 0xffff0000, v21
	v_lshlrev_b32_e32 v34, 16, v22
	v_and_b32_e32 v35, 0xffff0000, v22
	v_lshlrev_b32_e32 v36, 16, v23
	v_and_b32_e32 v37, 0xffff0000, v23
	v_mul_f32_e32 v30, v28, v30
	v_mul_f32_e32 v31, v28, v31
	v_mul_f32_e32 v32, v28, v32
	v_mul_f32_e32 v33, v28, v33
	v_mul_f32_e32 v34, v28, v34
	v_mul_f32_e32 v35, v28, v35
	v_mul_f32_e32 v36, v28, v36
	v_mul_f32_e32 v37, v28, v37
	v_mul_f32_e32 v64, v40, v30
	v_mul_f32_e32 v65, v41, v31
	v_mul_f32_e32 v66, v42, v32
	v_mul_f32_e32 v67, v43, v33
	v_mul_f32_e32 v68, v44, v34
	v_mul_f32_e32 v69, v45, v35
	v_mul_f32_e32 v70, v46, v36
	v_mul_f32_e32 v71, v47, v37
	v_lshlrev_b32_e32 v30, 16, v24
	v_and_b32_e32 v31, 0xffff0000, v24
	v_lshlrev_b32_e32 v32, 16, v25
	v_and_b32_e32 v33, 0xffff0000, v25
	v_lshlrev_b32_e32 v34, 16, v26
	v_and_b32_e32 v35, 0xffff0000, v26
	v_lshlrev_b32_e32 v36, 16, v27
	v_and_b32_e32 v37, 0xffff0000, v27
	v_mul_f32_e32 v30, v28, v30
	v_mul_f32_e32 v31, v28, v31
	v_mul_f32_e32 v32, v28, v32
	v_mul_f32_e32 v33, v28, v33
	v_mul_f32_e32 v34, v28, v34
	v_mul_f32_e32 v35, v28, v35
	v_mul_f32_e32 v36, v28, v36
	v_mul_f32_e32 v37, v28, v37
	v_mul_f32_e32 v72, v48, v30
	v_mul_f32_e32 v73, v49, v31
	v_mul_f32_e32 v74, v50, v32
	v_mul_f32_e32 v75, v51, v33
	v_mul_f32_e32 v76, v52, v34
	v_mul_f32_e32 v77, v53, v35
	v_mul_f32_e32 v78, v54, v36
	v_mul_f32_e32 v79, v55, v37
	s_add_i32 s12, s2, 0x1000
	s_lshl_b32 s13, s12, 12
	s_add_u32 s18, s6, s13
	s_addc_u32 s19, s7, 0
	global_store_dwordx4 v62, v[64:67], s[18:19]
	global_store_dwordx4 v62, v[68:71], s[18:19] offset:16
	global_store_dwordx4 v62, v[72:75], s[18:19] offset:2048
	global_store_dwordx4 v62, v[76:79], s[18:19] offset:2064
	s_add_i32 s12, s2, 0x2800
	s_lshl_b32 s13, s12, 11
	s_add_u32 s14, s10, s13
	s_addc_u32 s15, s11, 0
	s_add_u32 s14, s14, 0x6b00000
	s_addc_u32 s15, s15, 0
	s_lshl_b32 s13, s12, 6
	s_add_u32 s16, s10, s13
	s_addc_u32 s17, s11, 0
	s_add_u32 s16, s16, 0xfe00000
	s_addc_u32 s17, s17, 0
	global_load_dwordx4 v[20:23], v61, s[14:15]
	global_load_dwordx4 v[24:27], v61, s[14:15] offset:1024
	global_load_dword v28, v63, s[16:17]
	s_waitcnt vmcnt(14)
	s_nop 0
	v_add_f32_dpp v8, v8, v8 row_ror:8 row_mask:0xf bank_mask:0xf
	s_nop 1
	v_add_f32_dpp v8, v8, v8 row_ror:4 row_mask:0xf bank_mask:0xf
	s_nop 1
	v_add_f32_dpp v8, v8, v8 row_ror:2 row_mask:0xf bank_mask:0xf
	s_nop 1
	v_add_f32_dpp v8, v8, v8 row_ror:1 row_mask:0xf bank_mask:0xf
	s_nop 1
	v_fmamk_f32 v8, v8, 0x3a800000, v59
	v_rsq_f32_e32 v8, v8
	v_lshlrev_b32_e32 v30, 16, v0
	v_and_b32_e32 v31, 0xffff0000, v0
	v_lshlrev_b32_e32 v32, 16, v1
	v_and_b32_e32 v33, 0xffff0000, v1
	v_lshlrev_b32_e32 v34, 16, v2
	v_and_b32_e32 v35, 0xffff0000, v2
	v_lshlrev_b32_e32 v36, 16, v3
	v_and_b32_e32 v37, 0xffff0000, v3
	v_mul_f32_e32 v30, v8, v30
	v_mul_f32_e32 v31, v8, v31
	v_mul_f32_e32 v32, v8, v32
	v_mul_f32_e32 v33, v8, v33
	v_mul_f32_e32 v34, v8, v34
	v_mul_f32_e32 v35, v8, v35
	v_mul_f32_e32 v36, v8, v36
	v_mul_f32_e32 v37, v8, v37
	v_mul_f32_e32 v80, v40, v30
	v_mul_f32_e32 v81, v41, v31
	v_mul_f32_e32 v82, v42, v32
	v_mul_f32_e32 v83, v43, v33
	v_mul_f32_e32 v84, v44, v34
	v_mul_f32_e32 v85, v45, v35
	v_mul_f32_e32 v86, v46, v36
	v_mul_f32_e32 v87, v47, v37
	v_lshlrev_b32_e32 v30, 16, v4
	v_and_b32_e32 v31, 0xffff0000, v4
	v_lshlrev_b32_e32 v32, 16, v5
	v_and_b32_e32 v33, 0xffff0000, v5
	v_lshlrev_b32_e32 v34, 16, v6
	v_and_b32_e32 v35, 0xffff0000, v6
	v_lshlrev_b32_e32 v36, 16, v7
	v_and_b32_e32 v37, 0xffff0000, v7
	v_mul_f32_e32 v30, v8, v30
	v_mul_f32_e32 v31, v8, v31
	v_mul_f32_e32 v32, v8, v32
	v_mul_f32_e32 v33, v8, v33
	v_mul_f32_e32 v34, v8, v34
	v_mul_f32_e32 v35, v8, v35
	v_mul_f32_e32 v36, v8, v36
	v_mul_f32_e32 v37, v8, v37
	v_mul_f32_e32 v88, v48, v30
	v_mul_f32_e32 v89, v49, v31
	v_mul_f32_e32 v90, v50, v32
	v_mul_f32_e32 v91, v51, v33
	v_mul_f32_e32 v92, v52, v34
	v_mul_f32_e32 v93, v53, v35
	v_mul_f32_e32 v94, v54, v36
	v_mul_f32_e32 v95, v55, v37
	s_add_i32 s12, s2, 0x1800
	s_lshl_b32 s13, s12, 12
	s_add_u32 s18, s6, s13
	s_addc_u32 s19, s7, 0
	global_store_dwordx4 v62, v[80:83], s[18:19]
	global_store_dwordx4 v62, v[84:87], s[18:19] offset:16
	global_store_dwordx4 v62, v[88:91], s[18:19] offset:2048
	global_store_dwordx4 v62, v[92:95], s[18:19] offset:2064
	s_add_i32 s12, s2, 0x3000
	s_lshl_b32 s13, s12, 11
	s_add_u32 s14, s10, s13
	s_addc_u32 s15, s11, 0
	s_add_u32 s14, s14, 0x6b00000
	s_addc_u32 s15, s15, 0
	s_lshl_b32 s13, s12, 6
	s_add_u32 s16, s10, s13
	s_addc_u32 s17, s11, 0
	s_add_u32 s16, s16, 0xfe00000
	s_addc_u32 s17, s17, 0
	global_load_dwordx4 v[0:3], v61, s[14:15]
	global_load_dwordx4 v[4:7], v61, s[14:15] offset:1024
	global_load_dword v8, v63, s[16:17]
	s_waitcnt vmcnt(14)
	s_nop 0
	v_add_f32_dpp v18, v18, v18 row_ror:8 row_mask:0xf bank_mask:0xf
	s_nop 1
	v_add_f32_dpp v18, v18, v18 row_ror:4 row_mask:0xf bank_mask:0xf
	s_nop 1
	v_add_f32_dpp v18, v18, v18 row_ror:2 row_mask:0xf bank_mask:0xf
	s_nop 1
	v_add_f32_dpp v18, v18, v18 row_ror:1 row_mask:0xf bank_mask:0xf
	s_nop 1
	v_fmamk_f32 v18, v18, 0x3a800000, v59
	v_rsq_f32_e32 v18, v18
	v_lshlrev_b32_e32 v30, 16, v10
	v_and_b32_e32 v31, 0xffff0000, v10
	v_lshlrev_b32_e32 v32, 16, v11
	v_and_b32_e32 v33, 0xffff0000, v11
	v_lshlrev_b32_e32 v34, 16, v12
	v_and_b32_e32 v35, 0xffff0000, v12
	v_lshlrev_b32_e32 v36, 16, v13
	v_and_b32_e32 v37, 0xffff0000, v13
	v_mul_f32_e32 v30, v18, v30
	v_mul_f32_e32 v31, v18, v31
	v_mul_f32_e32 v32, v18, v32
	v_mul_f32_e32 v33, v18, v33
	v_mul_f32_e32 v34, v18, v34
	v_mul_f32_e32 v35, v18, v35
	v_mul_f32_e32 v36, v18, v36
	v_mul_f32_e32 v37, v18, v37
	v_mul_f32_e32 v64, v40, v30
	v_mul_f32_e32 v65, v41, v31
	v_mul_f32_e32 v66, v42, v32
	v_mul_f32_e32 v67, v43, v33
	v_mul_f32_e32 v68, v44, v34
	v_mul_f32_e32 v69, v45, v35
	v_mul_f32_e32 v70, v46, v36
	v_mul_f32_e32 v71, v47, v37
	v_lshlrev_b32_e32 v30, 16, v14
	v_and_b32_e32 v31, 0xffff0000, v14
	v_lshlrev_b32_e32 v32, 16, v15
	v_and_b32_e32 v33, 0xffff0000, v15
	v_lshlrev_b32_e32 v34, 16, v16
	v_and_b32_e32 v35, 0xffff0000, v16
	v_lshlrev_b32_e32 v36, 16, v17
	v_and_b32_e32 v37, 0xffff0000, v17
	v_mul_f32_e32 v30, v18, v30
	v_mul_f32_e32 v31, v18, v31
	v_mul_f32_e32 v32, v18, v32
	v_mul_f32_e32 v33, v18, v33
	v_mul_f32_e32 v34, v18, v34
	v_mul_f32_e32 v35, v18, v35
	v_mul_f32_e32 v36, v18, v36
	v_mul_f32_e32 v37, v18, v37
	v_mul_f32_e32 v72, v48, v30
	v_mul_f32_e32 v73, v49, v31
	v_mul_f32_e32 v74, v50, v32
	v_mul_f32_e32 v75, v51, v33
	v_mul_f32_e32 v76, v52, v34
	v_mul_f32_e32 v77, v53, v35
	v_mul_f32_e32 v78, v54, v36
	v_mul_f32_e32 v79, v55, v37
	s_add_i32 s12, s2, 0x2000
	s_lshl_b32 s13, s12, 12
	s_add_u32 s18, s6, s13
	s_addc_u32 s19, s7, 0
	global_store_dwordx4 v62, v[64:67], s[18:19]
	global_store_dwordx4 v62, v[68:71], s[18:19] offset:16
	global_store_dwordx4 v62, v[72:75], s[18:19] offset:2048
	global_store_dwordx4 v62, v[76:79], s[18:19] offset:2064
	s_add_i32 s12, s2, 0x3800
	s_lshl_b32 s13, s12, 11
	s_add_u32 s14, s10, s13
	s_addc_u32 s15, s11, 0
	s_add_u32 s14, s14, 0x6b00000
	s_addc_u32 s15, s15, 0
	s_lshl_b32 s13, s12, 6
	s_add_u32 s16, s10, s13
	s_addc_u32 s17, s11, 0
	s_add_u32 s16, s16, 0xfe00000
	s_addc_u32 s17, s17, 0
	global_load_dwordx4 v[10:13], v61, s[14:15]
	global_load_dwordx4 v[14:17], v61, s[14:15] offset:1024
	global_load_dword v18, v63, s[16:17]
	s_waitcnt vmcnt(14)
	s_nop 0
	v_add_f32_dpp v28, v28, v28 row_ror:8 row_mask:0xf bank_mask:0xf
	s_nop 1
	v_add_f32_dpp v28, v28, v28 row_ror:4 row_mask:0xf bank_mask:0xf
	s_nop 1
	v_add_f32_dpp v28, v28, v28 row_ror:2 row_mask:0xf bank_mask:0xf
	s_nop 1
	v_add_f32_dpp v28, v28, v28 row_ror:1 row_mask:0xf bank_mask:0xf
	s_nop 1
	v_fmamk_f32 v28, v28, 0x3a800000, v59
	v_rsq_f32_e32 v28, v28
	v_lshlrev_b32_e32 v30, 16, v20
	v_and_b32_e32 v31, 0xffff0000, v20
	v_lshlrev_b32_e32 v32, 16, v21
	v_and_b32_e32 v33, 0xffff0000, v21
	v_lshlrev_b32_e32 v34, 16, v22
	v_and_b32_e32 v35, 0xffff0000, v22
	v_lshlrev_b32_e32 v36, 16, v23
	v_and_b32_e32 v37, 0xffff0000, v23
	v_mul_f32_e32 v30, v28, v30
	v_mul_f32_e32 v31, v28, v31
	v_mul_f32_e32 v32, v28, v32
	v_mul_f32_e32 v33, v28, v33
	v_mul_f32_e32 v34, v28, v34
	v_mul_f32_e32 v35, v28, v35
	v_mul_f32_e32 v36, v28, v36
	v_mul_f32_e32 v37, v28, v37
	v_mul_f32_e32 v80, v40, v30
	v_mul_f32_e32 v81, v41, v31
	v_mul_f32_e32 v82, v42, v32
	v_mul_f32_e32 v83, v43, v33
	v_mul_f32_e32 v84, v44, v34
	v_mul_f32_e32 v85, v45, v35
	v_mul_f32_e32 v86, v46, v36
	v_mul_f32_e32 v87, v47, v37
	v_lshlrev_b32_e32 v30, 16, v24
	v_and_b32_e32 v31, 0xffff0000, v24
	v_lshlrev_b32_e32 v32, 16, v25
	v_and_b32_e32 v33, 0xffff0000, v25
	v_lshlrev_b32_e32 v34, 16, v26
	v_and_b32_e32 v35, 0xffff0000, v26
	v_lshlrev_b32_e32 v36, 16, v27
	v_and_b32_e32 v37, 0xffff0000, v27
	v_mul_f32_e32 v30, v28, v30
	v_mul_f32_e32 v31, v28, v31
	v_mul_f32_e32 v32, v28, v32
	v_mul_f32_e32 v33, v28, v33
	v_mul_f32_e32 v34, v28, v34
	v_mul_f32_e32 v35, v28, v35
	v_mul_f32_e32 v36, v28, v36
	v_mul_f32_e32 v37, v28, v37
	v_mul_f32_e32 v88, v48, v30
	v_mul_f32_e32 v89, v49, v31
	v_mul_f32_e32 v90, v50, v32
	v_mul_f32_e32 v91, v51, v33
	v_mul_f32_e32 v92, v52, v34
	v_mul_f32_e32 v93, v53, v35
	v_mul_f32_e32 v94, v54, v36
	v_mul_f32_e32 v95, v55, v37
	s_add_i32 s12, s2, 0x2800
	s_lshl_b32 s13, s12, 12
	s_add_u32 s18, s6, s13
	s_addc_u32 s19, s7, 0
	global_store_dwordx4 v62, v[80:83], s[18:19]
	global_store_dwordx4 v62, v[84:87], s[18:19] offset:16
	global_store_dwordx4 v62, v[88:91], s[18:19] offset:2048
	global_store_dwordx4 v62, v[92:95], s[18:19] offset:2064
	s_waitcnt vmcnt(11)
	s_nop 0
	v_add_f32_dpp v8, v8, v8 row_ror:8 row_mask:0xf bank_mask:0xf
	s_nop 1
	v_add_f32_dpp v8, v8, v8 row_ror:4 row_mask:0xf bank_mask:0xf
	s_nop 1
	v_add_f32_dpp v8, v8, v8 row_ror:2 row_mask:0xf bank_mask:0xf
	s_nop 1
	v_add_f32_dpp v8, v8, v8 row_ror:1 row_mask:0xf bank_mask:0xf
	s_nop 1
	v_fmamk_f32 v8, v8, 0x3a800000, v59
	v_rsq_f32_e32 v8, v8
	v_lshlrev_b32_e32 v30, 16, v0
	v_and_b32_e32 v31, 0xffff0000, v0
	v_lshlrev_b32_e32 v32, 16, v1
	v_and_b32_e32 v33, 0xffff0000, v1
	v_lshlrev_b32_e32 v34, 16, v2
	v_and_b32_e32 v35, 0xffff0000, v2
	v_lshlrev_b32_e32 v36, 16, v3
	v_and_b32_e32 v37, 0xffff0000, v3
	v_mul_f32_e32 v30, v8, v30
	v_mul_f32_e32 v31, v8, v31
	v_mul_f32_e32 v32, v8, v32
	v_mul_f32_e32 v33, v8, v33
	v_mul_f32_e32 v34, v8, v34
	v_mul_f32_e32 v35, v8, v35
	v_mul_f32_e32 v36, v8, v36
	v_mul_f32_e32 v37, v8, v37
	v_mul_f32_e32 v64, v40, v30
	v_mul_f32_e32 v65, v41, v31
	v_mul_f32_e32 v66, v42, v32
	v_mul_f32_e32 v67, v43, v33
	v_mul_f32_e32 v68, v44, v34
	v_mul_f32_e32 v69, v45, v35
	v_mul_f32_e32 v70, v46, v36
	v_mul_f32_e32 v71, v47, v37
	v_lshlrev_b32_e32 v30, 16, v4
	v_and_b32_e32 v31, 0xffff0000, v4
	v_lshlrev_b32_e32 v32, 16, v5
	v_and_b32_e32 v33, 0xffff0000, v5
	v_lshlrev_b32_e32 v34, 16, v6
	v_and_b32_e32 v35, 0xffff0000, v6
	v_lshlrev_b32_e32 v36, 16, v7
	v_and_b32_e32 v37, 0xffff0000, v7
	v_mul_f32_e32 v30, v8, v30
	v_mul_f32_e32 v31, v8, v31
	v_mul_f32_e32 v32, v8, v32
	v_mul_f32_e32 v33, v8, v33
	v_mul_f32_e32 v34, v8, v34
	v_mul_f32_e32 v35, v8, v35
	v_mul_f32_e32 v36, v8, v36
	v_mul_f32_e32 v37, v8, v37
	v_mul_f32_e32 v72, v48, v30
	v_mul_f32_e32 v73, v49, v31
	v_mul_f32_e32 v74, v50, v32
	v_mul_f32_e32 v75, v51, v33
	v_mul_f32_e32 v76, v52, v34
	v_mul_f32_e32 v77, v53, v35
	v_mul_f32_e32 v78, v54, v36
	v_mul_f32_e32 v79, v55, v37
	s_add_i32 s12, s2, 0x3000
	s_lshl_b32 s13, s12, 12
	s_add_u32 s18, s6, s13
	s_addc_u32 s19, s7, 0
	global_store_dwordx4 v62, v[64:67], s[18:19]
	global_store_dwordx4 v62, v[68:71], s[18:19] offset:16
	global_store_dwordx4 v62, v[72:75], s[18:19] offset:2048
	global_store_dwordx4 v62, v[76:79], s[18:19] offset:2064
	s_waitcnt vmcnt(8)
	s_nop 0
	v_add_f32_dpp v18, v18, v18 row_ror:8 row_mask:0xf bank_mask:0xf
	s_nop 1
	v_add_f32_dpp v18, v18, v18 row_ror:4 row_mask:0xf bank_mask:0xf
	s_nop 1
	v_add_f32_dpp v18, v18, v18 row_ror:2 row_mask:0xf bank_mask:0xf
	s_nop 1
	v_add_f32_dpp v18, v18, v18 row_ror:1 row_mask:0xf bank_mask:0xf
	s_nop 1
	v_fmamk_f32 v18, v18, 0x3a800000, v59
	v_rsq_f32_e32 v18, v18
	v_lshlrev_b32_e32 v30, 16, v10
	v_and_b32_e32 v31, 0xffff0000, v10
	v_lshlrev_b32_e32 v32, 16, v11
	v_and_b32_e32 v33, 0xffff0000, v11
	v_lshlrev_b32_e32 v34, 16, v12
	v_and_b32_e32 v35, 0xffff0000, v12
	v_lshlrev_b32_e32 v36, 16, v13
	v_and_b32_e32 v37, 0xffff0000, v13
	v_mul_f32_e32 v30, v18, v30
	v_mul_f32_e32 v31, v18, v31
	v_mul_f32_e32 v32, v18, v32
	v_mul_f32_e32 v33, v18, v33
	v_mul_f32_e32 v34, v18, v34
	v_mul_f32_e32 v35, v18, v35
	v_mul_f32_e32 v36, v18, v36
	v_mul_f32_e32 v37, v18, v37
	v_mul_f32_e32 v80, v40, v30
	v_mul_f32_e32 v81, v41, v31
	v_mul_f32_e32 v82, v42, v32
	v_mul_f32_e32 v83, v43, v33
	v_mul_f32_e32 v84, v44, v34
	v_mul_f32_e32 v85, v45, v35
	v_mul_f32_e32 v86, v46, v36
	v_mul_f32_e32 v87, v47, v37
	v_lshlrev_b32_e32 v30, 16, v14
	v_and_b32_e32 v31, 0xffff0000, v14
	v_lshlrev_b32_e32 v32, 16, v15
	v_and_b32_e32 v33, 0xffff0000, v15
	v_lshlrev_b32_e32 v34, 16, v16
	v_and_b32_e32 v35, 0xffff0000, v16
	v_lshlrev_b32_e32 v36, 16, v17
	v_and_b32_e32 v37, 0xffff0000, v17
	v_mul_f32_e32 v30, v18, v30
	v_mul_f32_e32 v31, v18, v31
	v_mul_f32_e32 v32, v18, v32
	v_mul_f32_e32 v33, v18, v33
	v_mul_f32_e32 v34, v18, v34
	v_mul_f32_e32 v35, v18, v35
	v_mul_f32_e32 v36, v18, v36
	v_mul_f32_e32 v37, v18, v37
	v_mul_f32_e32 v88, v48, v30
	v_mul_f32_e32 v89, v49, v31
	v_mul_f32_e32 v90, v50, v32
	v_mul_f32_e32 v91, v51, v33
	v_mul_f32_e32 v92, v52, v34
	v_mul_f32_e32 v93, v53, v35
	v_mul_f32_e32 v94, v54, v36
	v_mul_f32_e32 v95, v55, v37
	s_add_i32 s12, s2, 0x3800
	s_lshl_b32 s13, s12, 12
	s_add_u32 s18, s6, s13
	s_addc_u32 s19, s7, 0
	global_store_dwordx4 v62, v[80:83], s[18:19]
	global_store_dwordx4 v62, v[84:87], s[18:19] offset:16
	global_store_dwordx4 v62, v[88:91], s[18:19] offset:2048
	global_store_dwordx4 v62, v[92:95], s[18:19] offset:2064
